# rows phases (LayerNorm + modulation): x / H streaming stores marked nt
# baseline (speedup 1.0000x reference)
.LBB0_26:
	s_or_b64 exec, exec, s[30:31]
	s_and_b64 s[0:1], exec, vcc
	v_lshlrev_b64 v[146:147], 12, v[176:177]
	v_lshlrev_b32_e32 v176, 16, v164
	v_and_b32_e32 v177, 0xffff0000, v164
	s_or_b64 s[6:7], s[0:1], s[6:7]
	s_waitcnt vmcnt(0)
	v_pk_mul_f32 v[126:127], v[126:127], v[176:177]
	s_mov_b32 s0, 0x3fd744fd
	v_pk_fma_f32 v[78:79], v[78:79], s[0:1], v[126:127] op_sel_hi:[1,0,1]
	v_lshlrev_b32_e32 v126, 16, v165
	v_and_b32_e32 v127, 0xffff0000, v165
	v_pk_mul_f32 v[126:127], v[128:129], v[126:127]
	v_lshl_add_u64 v[146:147], v[178:179], 0, v[146:147]
	v_pk_fma_f32 v[80:81], v[80:81], s[0:1], v[126:127] op_sel_hi:[1,0,1]
	v_lshlrev_b32_e32 v126, 16, v152
	v_and_b32_e32 v127, 0xffff0000, v152
	s_waitcnt vmcnt(2)
	v_pk_mul_f32 v[122:123], v[122:123], v[126:127]
	s_mov_b32 s78, 0x800000
	v_pk_fma_f32 v[74:75], v[74:75], s[0:1], v[122:123] op_sel_hi:[1,0,1]
	v_lshlrev_b32_e32 v122, 16, v153
	v_and_b32_e32 v123, 0xffff0000, v153
	v_pk_mul_f32 v[122:123], v[124:125], v[122:123]
	v_mov_b64_e32 v[152:153], v[170:171]
	v_pk_fma_f32 v[76:77], v[76:77], s[0:1], v[122:123] op_sel_hi:[1,0,1]
	v_lshlrev_b32_e32 v122, 16, v150
	v_and_b32_e32 v123, 0xffff0000, v150
	s_waitcnt vmcnt(1)
	v_pk_mul_f32 v[118:119], v[118:119], v[122:123]
	v_mov_b64_e32 v[164:165], v[168:169]
	v_pk_fma_f32 v[58:59], v[58:59], s[0:1], v[118:119] op_sel_hi:[1,0,1]
	v_lshlrev_b32_e32 v118, 16, v151
	v_and_b32_e32 v119, 0xffff0000, v151
	v_pk_mul_f32 v[118:119], v[120:121], v[118:119]
	v_mov_b64_e32 v[150:151], v[172:173]
	v_pk_fma_f32 v[60:61], v[60:61], s[0:1], v[118:119] op_sel_hi:[1,0,1]
	v_lshlrev_b32_e32 v118, 16, v148
	v_and_b32_e32 v119, 0xffff0000, v148
	s_waitcnt vmcnt(0)
	v_pk_mul_f32 v[114:115], v[114:115], v[118:119]
	s_nop 0
	v_pk_fma_f32 v[50:51], v[50:51], s[0:1], v[114:115] op_sel_hi:[1,0,1]
	v_lshlrev_b32_e32 v114, 16, v149
	v_and_b32_e32 v115, 0xffff0000, v149
	v_pk_mul_f32 v[114:115], v[116:117], v[114:115]
	v_lshlrev_b32_e32 v116, 16, v140
	v_and_b32_e32 v117, 0xffff0000, v140
	v_pk_mul_f32 v[110:111], v[110:111], v[116:117]
	v_pk_fma_f32 v[52:53], v[52:53], s[0:1], v[114:115] op_sel_hi:[1,0,1]
	v_pk_fma_f32 v[46:47], v[46:47], s[0:1], v[110:111] op_sel_hi:[1,0,1]
	v_lshlrev_b32_e32 v110, 16, v141
	v_and_b32_e32 v111, 0xffff0000, v141
	v_pk_mul_f32 v[110:111], v[112:113], v[110:111]
	v_lshlrev_b64 v[114:115], 12, v[166:167]
	v_pk_fma_f32 v[48:49], v[48:49], s[0:1], v[110:111] op_sel_hi:[1,0,1]
	v_lshlrev_b32_e32 v110, 16, v138
	v_and_b32_e32 v111, 0xffff0000, v138
	v_pk_mul_f32 v[106:107], v[106:107], v[110:111]
	v_mov_b64_e32 v[148:149], v[174:175]
	v_pk_fma_f32 v[42:43], v[42:43], s[0:1], v[106:107] op_sel_hi:[1,0,1]
	v_lshlrev_b32_e32 v106, 16, v139
	v_and_b32_e32 v107, 0xffff0000, v139
	v_pk_mul_f32 v[106:107], v[108:109], v[106:107]
	v_mov_b64_e32 v[138:139], v[156:157]
	v_pk_fma_f32 v[44:45], v[44:45], s[0:1], v[106:107] op_sel_hi:[1,0,1]
	v_lshlrev_b32_e32 v106, 16, v136
	v_and_b32_e32 v107, 0xffff0000, v136
	v_pk_mul_f32 v[94:95], v[94:95], v[106:107]
	v_mov_b64_e32 v[140:141], v[154:155]
	v_pk_fma_f32 v[38:39], v[38:39], s[0:1], v[94:95] op_sel_hi:[1,0,1]
	v_lshlrev_b32_e32 v94, 16, v137
	v_and_b32_e32 v95, 0xffff0000, v137
	v_pk_mul_f32 v[94:95], v[96:97], v[94:95]
	v_mov_b64_e32 v[136:137], v[158:159]
	v_pk_fma_f32 v[40:41], v[40:41], s[0:1], v[94:95] op_sel_hi:[1,0,1]
	v_lshlrev_b32_e32 v94, 16, v134
	v_and_b32_e32 v95, 0xffff0000, v134
	v_pk_mul_f32 v[82:83], v[82:83], v[94:95]
	s_nop 0
	v_pk_fma_f32 v[34:35], v[34:35], s[0:1], v[82:83] op_sel_hi:[1,0,1]
	v_lshlrev_b32_e32 v82, 16, v135
	v_and_b32_e32 v83, 0xffff0000, v135
	v_pk_mul_f32 v[82:83], v[84:85], v[82:83]
	v_add_f32_e32 v84, v42, v43
	v_pk_fma_f32 v[36:37], v[36:37], s[0:1], v[82:83] op_sel_hi:[1,0,1]
	v_add_f32_e32 v82, v48, v49
	v_add_f32_e32 v83, v46, v47
	v_add_f32_e32 v82, v83, v82
	v_add_f32_e32 v83, v44, v45
	v_add_f32_e32 v82, 0, v82
	v_add_f32_e32 v83, v84, v83
	v_add_f32_e32 v82, v82, v83
	v_add_f32_e32 v83, v40, v41
	v_add_f32_e32 v84, v38, v39
	v_add_f32_e32 v83, v84, v83
	v_add_f32_e32 v82, v82, v83
	v_add_f32_e32 v83, v36, v37
	v_add_f32_e32 v84, v34, v35
	v_add_f32_e32 v83, v84, v83
	v_add_f32_e32 v82, v82, v83
	v_add_f32_e32 v83, v80, v81
	v_add_f32_e32 v84, v78, v79
	v_add_f32_e32 v83, v84, v83
	v_add_f32_e32 v84, v76, v77
	v_add_f32_e32 v85, v74, v75
	v_add_f32_e32 v83, 0, v83
	v_add_f32_e32 v84, v85, v84
	v_add_f32_e32 v83, v83, v84
	v_add_f32_e32 v84, v60, v61
	v_add_f32_e32 v85, v58, v59
	v_add_f32_dpp v82, v82, v82 quad_perm:[1,0,3,2] row_mask:0xf bank_mask:0xf bound_ctrl:1
	v_add_f32_e32 v84, v85, v84
	v_add_f32_e32 v83, v83, v84
	v_add_f32_dpp v82, v82, v82 quad_perm:[2,3,0,1] row_mask:0xf bank_mask:0xf bound_ctrl:1
	v_add_f32_e32 v84, v52, v53
	v_add_f32_e32 v85, v50, v51
	v_add_f32_dpp v82, v82, v82 row_half_mirror row_mask:0xf bank_mask:0xf bound_ctrl:1
	v_add_f32_e32 v84, v85, v84
	v_add_f32_e32 v83, v83, v84
	v_add_f32_dpp v82, v82, v82 row_mirror row_mask:0xf bank_mask:0xf bound_ctrl:1
	v_mov_b32_e32 v84, v82
	s_nop 1
	v_permlane16_swap_b32_e32 v82, v84
	v_add_f32_dpp v83, v83, v83 quad_perm:[1,0,3,2] row_mask:0xf bank_mask:0xf bound_ctrl:1
	v_add_f32_e32 v82, v82, v84
	v_mov_b32_e32 v84, v82
	v_add_f32_dpp v83, v83, v83 quad_perm:[2,3,0,1] row_mask:0xf bank_mask:0xf bound_ctrl:1
	s_nop 0
	v_permlane32_swap_b32_e32 v82, v84
	v_add_f32_dpp v83, v83, v83 row_half_mirror row_mask:0xf bank_mask:0xf bound_ctrl:1
	v_add_f32_e32 v82, v82, v84
	v_mul_f32_e32 v82, 0x3a800000, v82
	v_add_f32_dpp v83, v83, v83 row_mirror row_mask:0xf bank_mask:0xf bound_ctrl:1
	v_mov_b32_e32 v84, v83
	s_nop 1
	v_permlane16_swap_b32_e32 v83, v84
	v_add_f32_e32 v83, v83, v84
	v_mov_b32_e32 v84, v83
	s_nop 1
	v_permlane32_swap_b32_e32 v83, v84
	v_add_f32_e32 v83, v83, v84
	v_pk_add_f32 v[46:47], v[46:47], v[82:83] op_sel_hi:[1,0] neg_lo:[0,1] neg_hi:[0,1]
	v_pk_add_f32 v[48:49], v[48:49], v[82:83] op_sel_hi:[1,0] neg_lo:[0,1] neg_hi:[0,1]
	v_pk_add_f32 v[42:43], v[42:43], v[82:83] op_sel_hi:[1,0] neg_lo:[0,1] neg_hi:[0,1]
	v_pk_add_f32 v[44:45], v[44:45], v[82:83] op_sel_hi:[1,0] neg_lo:[0,1] neg_hi:[0,1]
	v_pk_mul_f32 v[94:95], v[46:47], v[46:47]
	v_pk_mul_f32 v[96:97], v[48:49], v[48:49]
	v_pk_mul_f32 v[106:107], v[42:43], v[42:43]
	v_pk_mul_f32 v[108:109], v[44:45], v[44:45]
	v_pk_add_f32 v[110:111], v[38:39], v[82:83] op_sel_hi:[1,0] neg_lo:[0,1] neg_hi:[0,1]
	v_pk_add_f32 v[112:113], v[40:41], v[82:83] op_sel_hi:[1,0] neg_lo:[0,1] neg_hi:[0,1]
	v_mul_f32_e32 v84, 0x3a800000, v83
	v_pk_mul_f32 v[38:39], v[110:111], v[110:111]
	v_pk_mul_f32 v[40:41], v[112:113], v[112:113]
	v_pk_add_f32 v[116:117], v[34:35], v[82:83] op_sel_hi:[1,0] neg_lo:[0,1] neg_hi:[0,1]
	v_pk_add_f32 v[82:83], v[36:37], v[82:83] op_sel_hi:[1,0] neg_lo:[0,1] neg_hi:[0,1]
	v_add_f32_e32 v85, v108, v109
	v_add_f32_e32 v106, v106, v107
	v_add_f32_e32 v96, v96, v97
	v_add_f32_e32 v94, v94, v95
	v_pk_mul_f32 v[34:35], v[116:117], v[116:117]
	v_pk_mul_f32 v[36:37], v[82:83], v[82:83]
	v_add_f32_e32 v85, v106, v85
	v_add_f32_e32 v94, v94, v96
	v_add_f32_e32 v40, v40, v41
	v_add_f32_e32 v38, v38, v39
	v_add_f32_e32 v85, v94, v85
	v_add_f32_e32 v38, v38, v40
	v_add_f32_e32 v36, v36, v37
	v_add_f32_e32 v34, v34, v35
	v_add_f32_e32 v38, v38, v85
	v_add_f32_e32 v34, v34, v36
	v_add_f32_e32 v34, v34, v38
	v_pk_add_f32 v[74:75], v[74:75], v[84:85] op_sel_hi:[1,0] neg_lo:[0,1] neg_hi:[0,1]
	v_pk_add_f32 v[76:77], v[76:77], v[84:85] op_sel_hi:[1,0] neg_lo:[0,1] neg_hi:[0,1]
	v_add_f32_dpp v34, v34, v34 quad_perm:[1,0,3,2] row_mask:0xf bank_mask:0xf bound_ctrl:1
	v_pk_add_f32 v[78:79], v[78:79], v[84:85] op_sel_hi:[1,0] neg_lo:[0,1] neg_hi:[0,1]
	v_pk_add_f32 v[80:81], v[80:81], v[84:85] op_sel_hi:[1,0] neg_lo:[0,1] neg_hi:[0,1]
	v_add_f32_dpp v34, v34, v34 quad_perm:[2,3,0,1] row_mask:0xf bank_mask:0xf bound_ctrl:1
	v_pk_mul_f32 v[94:95], v[74:75], v[74:75]
	v_pk_mul_f32 v[96:97], v[76:77], v[76:77]
	v_add_f32_dpp v34, v34, v34 row_half_mirror row_mask:0xf bank_mask:0xf bound_ctrl:1
	v_pk_mul_f32 v[38:39], v[78:79], v[78:79]
	v_pk_mul_f32 v[40:41], v[80:81], v[80:81]
	v_add_f32_dpp v34, v34, v34 row_mirror row_mask:0xf bank_mask:0xf bound_ctrl:1
	v_mov_b32_e32 v35, v34
	s_nop 1
	v_permlane16_swap_b32_e32 v34, v35
	v_add_f32_e32 v35, v34, v35
	v_add_f32_e32 v34, v96, v97
	v_add_f32_e32 v36, v94, v95
	v_pk_add_f32 v[58:59], v[58:59], v[84:85] op_sel_hi:[1,0] neg_lo:[0,1] neg_hi:[0,1]
	v_pk_add_f32 v[60:61], v[60:61], v[84:85] op_sel_hi:[1,0] neg_lo:[0,1] neg_hi:[0,1]
	v_add_f32_e32 v34, v36, v34
	v_add_f32_e32 v36, v40, v41
	v_add_f32_e32 v38, v38, v39
	v_pk_mul_f32 v[106:107], v[58:59], v[58:59]
	v_pk_mul_f32 v[108:109], v[60:61], v[60:61]
	v_add_f32_e32 v36, v38, v36
	v_pk_add_f32 v[50:51], v[50:51], v[84:85] op_sel_hi:[1,0] neg_lo:[0,1] neg_hi:[0,1]
	v_pk_add_f32 v[52:53], v[52:53], v[84:85] op_sel_hi:[1,0] neg_lo:[0,1] neg_hi:[0,1]
	v_add_f32_e32 v34, v36, v34
	v_add_f32_e32 v36, v108, v109
	v_add_f32_e32 v38, v106, v107
	v_pk_mul_f32 v[118:119], v[50:51], v[50:51]
	v_pk_mul_f32 v[84:85], v[52:53], v[52:53]
	v_add_f32_e32 v36, v38, v36
	v_add_f32_e32 v34, v36, v34
	v_add_f32_e32 v36, v84, v85
	v_add_f32_e32 v38, v118, v119
	v_add_f32_e32 v36, v38, v36
	v_add_f32_e32 v34, v36, v34
	v_mov_b32_e32 v37, v35
	s_nop 1
	v_permlane32_swap_b32_e32 v35, v37
	v_add_f32_dpp v34, v34, v34 quad_perm:[1,0,3,2] row_mask:0xf bank_mask:0xf bound_ctrl:1
	s_mov_b32 s0, 0x3a800000
	v_lshl_add_u64 v[96:97], v[146:147], 0, v[0:1]
	v_add_f32_dpp v34, v34, v34 quad_perm:[2,3,0,1] row_mask:0xf bank_mask:0xf bound_ctrl:1
	v_mov_b64_e32 v[134:135], v[160:161]
	v_mov_b32_e32 v146, v144
	v_add_f32_dpp v34, v34, v34 row_half_mirror row_mask:0xf bank_mask:0xf bound_ctrl:1
	s_nop 1
	v_add_f32_dpp v34, v34, v34 row_mirror row_mask:0xf bank_mask:0xf bound_ctrl:1
	v_mov_b32_e32 v36, v34
	s_nop 1
	v_permlane16_swap_b32_e32 v34, v36
	v_add_f32_e32 v34, v34, v36
	v_mov_b32_e32 v36, v34
	s_nop 1
	v_permlane32_swap_b32_e32 v34, v36
	v_pk_add_f32 v[34:35], v[34:35], v[36:37]
	s_nop 0
	v_pk_fma_f32 v[84:85], v[34:35], s[0:1], v[162:163] op_sel_hi:[1,0,0]
	s_mov_b32 s0, 0x800000
	v_mul_f32_e32 v34, 0x4b800000, v85
	v_cmp_gt_f32_e32 vcc, s0, v85
	s_nop 1
	v_cndmask_b32_e32 v34, v85, v34, vcc
	v_rsq_f32_e32 v36, v34
	v_lshl_add_u64 v[34:35], v[142:143], 0, v[114:115]
	v_lshl_add_u64 v[94:95], v[34:35], 0, v[0:1]
	v_mul_f32_e32 v34, 0x45800000, v36
	v_cndmask_b32_e32 v106, v36, v34, vcc
	v_pk_mul_f32 v[34:35], v[46:47], v[106:107] op_sel_hi:[1,0]
	v_pk_mul_f32 v[36:37], v[48:49], v[106:107] op_sel_hi:[1,0]
	v_pk_fma_f32 v[34:35], v[2:3], v[34:35], v[10:11]
	v_pk_fma_f32 v[36:37], v[4:5], v[36:37], v[12:13]
	global_store_dwordx4 v[94:95], v[34:37], off nt
	v_cmp_gt_f32_e32 vcc, s0, v84
	v_pk_mul_f32 v[38:39], v[42:43], v[106:107] op_sel_hi:[1,0]
	v_mul_f32_e32 v34, 0x4b800000, v84
	v_cndmask_b32_e32 v34, v84, v34, vcc
	v_rsq_f32_e32 v34, v34
	v_pk_mul_f32 v[40:41], v[44:45], v[106:107] op_sel_hi:[1,0]
	v_pk_mul_f32 v[48:49], v[82:83], v[106:107] op_sel_hi:[1,0]
	v_pk_fma_f32 v[38:39], v[6:7], v[38:39], v[14:15]
	v_pk_fma_f32 v[40:41], v[8:9], v[40:41], v[16:17]
	v_pk_mul_f32 v[42:43], v[110:111], v[106:107] op_sel_hi:[1,0]
	v_pk_mul_f32 v[44:45], v[112:113], v[106:107] op_sel_hi:[1,0]
	v_pk_mul_f32 v[46:47], v[116:117], v[106:107] op_sel_hi:[1,0]
	v_pk_fma_f32 v[48:49], v[24:25], v[48:49], v[32:33]
	v_mul_f32_e32 v35, 0x45800000, v34
	v_pk_fma_f32 v[42:43], v[18:19], v[42:43], v[26:27]
	v_pk_fma_f32 v[44:45], v[20:21], v[44:45], v[28:29]
	v_pk_fma_f32 v[46:47], v[22:23], v[46:47], v[30:31]
	global_store_dwordx4 v[94:95], v[38:41], off offset:1024 nt
	global_store_dwordx4 v[94:95], v[42:45], off offset:2048 nt
	global_store_dwordx4 v[94:95], v[46:49], off offset:3072 nt
	s_nop 1
	v_cndmask_b32_e32 v48, v34, v35, vcc
	v_pk_mul_f32 v[34:35], v[78:79], v[48:49] op_sel_hi:[1,0]
	v_pk_mul_f32 v[36:37], v[80:81], v[48:49] op_sel_hi:[1,0]
	v_pk_mul_f32 v[38:39], v[74:75], v[48:49] op_sel_hi:[1,0]
	v_pk_mul_f32 v[40:41], v[76:77], v[48:49] op_sel_hi:[1,0]
	v_pk_mul_f32 v[42:43], v[58:59], v[48:49] op_sel_hi:[1,0]
	v_pk_mul_f32 v[44:45], v[60:61], v[48:49] op_sel_hi:[1,0]
	v_pk_mul_f32 v[46:47], v[50:51], v[48:49] op_sel_hi:[1,0]
	v_pk_mul_f32 v[48:49], v[52:53], v[48:49] op_sel_hi:[1,0]
	v_pk_fma_f32 v[34:35], v[2:3], v[34:35], v[10:11]
	v_pk_fma_f32 v[36:37], v[4:5], v[36:37], v[12:13]
	v_pk_fma_f32 v[38:39], v[6:7], v[38:39], v[14:15]
	v_pk_fma_f32 v[40:41], v[8:9], v[40:41], v[16:17]
	v_pk_fma_f32 v[42:43], v[18:19], v[42:43], v[26:27]
	v_pk_fma_f32 v[44:45], v[20:21], v[44:45], v[28:29]
	v_pk_fma_f32 v[46:47], v[22:23], v[46:47], v[30:31]
	v_pk_fma_f32 v[48:49], v[24:25], v[48:49], v[32:33]
	global_store_dwordx4 v[96:97], v[34:37], off nt
	global_store_dwordx4 v[96:97], v[38:41], off offset:1024 nt
	global_store_dwordx4 v[96:97], v[42:45], off offset:2048 nt
	global_store_dwordx4 v[96:97], v[46:49], off offset:3072 nt
	v_mov_b64_e32 v[38:39], v[62:63]
	v_mov_b64_e32 v[42:43], v[66:67]
	v_mov_b64_e32 v[46:47], v[70:71]
	v_mov_b64_e32 v[48:49], v[72:73]
	v_mov_b64_e32 v[44:45], v[68:69]
	v_mov_b64_e32 v[40:41], v[64:65]
	v_mov_b64_e32 v[34:35], v[54:55]
	v_mov_b64_e32 v[36:37], v[56:57]
	v_mov_b64_e32 v[78:79], v[86:87]
	v_mov_b64_e32 v[80:81], v[88:89]
	v_mov_b64_e32 v[74:75], v[90:91]
	v_mov_b64_e32 v[76:77], v[92:93]
	v_mov_b64_e32 v[58:59], v[98:99]
	v_mov_b64_e32 v[60:61], v[100:101]
	v_mov_b64_e32 v[50:51], v[102:103]
	v_mov_b64_e32 v[52:53], v[104:105]
	s_andn2_b64 exec, exec, s[6:7]
	s_cbranch_execz .LBB0_44

.LBB0_161:
	s_or_b64 exec, exec, s[30:31]
	s_and_b64 s[0:1], exec, vcc
	v_lshlrev_b64 v[180:181], 12, v[210:211]
	v_lshlrev_b32_e32 v210, 16, v196
	v_and_b32_e32 v211, 0xffff0000, v196
	s_or_b64 s[6:7], s[0:1], s[6:7]
	v_pk_mul_f32 v[158:159], v[158:159], v[210:211]
	s_mov_b32 s0, 0x3fd744fd
	v_pk_fma_f32 v[98:99], v[98:99], s[0:1], v[158:159] op_sel_hi:[1,0,1]
	v_lshlrev_b32_e32 v158, 16, v197
	v_and_b32_e32 v159, 0xffff0000, v197
	v_pk_mul_f32 v[158:159], v[160:161], v[158:159]
	v_pk_add_f32 v[126:127], v[126:127], 1.0 op_sel_hi:[1,0]
	v_pk_fma_f32 v[100:101], v[100:101], s[0:1], v[158:159] op_sel_hi:[1,0,1]
	v_lshlrev_b32_e32 v158, 16, v194
	v_and_b32_e32 v159, 0xffff0000, v194
	v_pk_mul_f32 v[154:155], v[154:155], v[158:159]
	v_pk_add_f32 v[128:129], v[128:129], 1.0 op_sel_hi:[1,0]
	v_pk_fma_f32 v[94:95], v[94:95], s[0:1], v[154:155] op_sel_hi:[1,0,1]
	v_lshlrev_b32_e32 v154, 16, v195
	v_and_b32_e32 v155, 0xffff0000, v195
	v_pk_mul_f32 v[154:155], v[156:157], v[154:155]
	v_pk_add_f32 v[118:119], v[118:119], 1.0 op_sel_hi:[1,0]
	v_pk_fma_f32 v[96:97], v[96:97], s[0:1], v[154:155] op_sel_hi:[1,0,1]
	v_lshlrev_b32_e32 v154, 16, v192
	v_and_b32_e32 v155, 0xffff0000, v192
	v_pk_mul_f32 v[150:151], v[150:151], v[154:155]
	v_pk_add_f32 v[120:121], v[120:121], 1.0 op_sel_hi:[1,0]
	v_pk_fma_f32 v[86:87], v[86:87], s[0:1], v[150:151] op_sel_hi:[1,0,1]
	v_lshlrev_b32_e32 v150, 16, v193
	v_and_b32_e32 v151, 0xffff0000, v193
	v_pk_mul_f32 v[150:151], v[152:153], v[150:151]
	v_pk_add_f32 v[122:123], v[122:123], 1.0 op_sel_hi:[1,0]
	v_pk_fma_f32 v[88:89], v[88:89], s[0:1], v[150:151] op_sel_hi:[1,0,1]
	v_lshlrev_b32_e32 v150, 16, v182
	v_and_b32_e32 v151, 0xffff0000, v182
	v_pk_mul_f32 v[146:147], v[146:147], v[150:151]
	v_pk_add_f32 v[124:125], v[124:125], 1.0 op_sel_hi:[1,0]
	v_pk_fma_f32 v[82:83], v[82:83], s[0:1], v[146:147] op_sel_hi:[1,0,1]
	v_lshlrev_b32_e32 v146, 16, v183
	v_and_b32_e32 v147, 0xffff0000, v183
	v_pk_mul_f32 v[146:147], v[148:149], v[146:147]
	v_lshlrev_b32_e32 v148, 16, v176
	v_and_b32_e32 v149, 0xffff0000, v176
	v_pk_mul_f32 v[142:143], v[142:143], v[148:149]
	v_pk_fma_f32 v[84:85], v[84:85], s[0:1], v[146:147] op_sel_hi:[1,0,1]
	v_pk_fma_f32 v[46:47], v[46:47], s[0:1], v[142:143] op_sel_hi:[1,0,1]
	v_lshlrev_b32_e32 v142, 16, v177
	v_and_b32_e32 v143, 0xffff0000, v177
	v_pk_mul_f32 v[142:143], v[144:145], v[142:143]
	v_lshlrev_b64 v[146:147], 12, v[198:199]
	v_pk_fma_f32 v[48:49], v[48:49], s[0:1], v[142:143] op_sel_hi:[1,0,1]
	v_lshlrev_b32_e32 v142, 16, v174
	v_and_b32_e32 v143, 0xffff0000, v174
	v_pk_mul_f32 v[138:139], v[138:139], v[142:143]
	v_lshl_add_u64 v[146:147], v[202:203], 0, v[146:147]
	v_pk_fma_f32 v[42:43], v[42:43], s[0:1], v[138:139] op_sel_hi:[1,0,1]
	v_lshlrev_b32_e32 v138, 16, v175
	v_and_b32_e32 v139, 0xffff0000, v175
	v_pk_mul_f32 v[138:139], v[140:141], v[138:139]
	v_pk_add_f32 v[90:91], v[90:91], 1.0 op_sel_hi:[1,0]
	v_pk_fma_f32 v[44:45], v[44:45], s[0:1], v[138:139] op_sel_hi:[1,0,1]
	v_lshlrev_b32_e32 v138, 16, v172
	v_and_b32_e32 v139, 0xffff0000, v172
	v_pk_mul_f32 v[134:135], v[134:135], v[138:139]
	v_pk_add_f32 v[92:93], v[92:93], 1.0 op_sel_hi:[1,0]
	v_pk_fma_f32 v[38:39], v[38:39], s[0:1], v[134:135] op_sel_hi:[1,0,1]
	v_lshlrev_b32_e32 v134, 16, v173
	v_and_b32_e32 v135, 0xffff0000, v173
	v_pk_mul_f32 v[134:135], v[136:137], v[134:135]
	v_lshl_add_u64 v[180:181], v[212:213], 0, v[180:181]
	v_pk_fma_f32 v[40:41], v[40:41], s[0:1], v[134:135] op_sel_hi:[1,0,1]
	v_lshlrev_b32_e32 v134, 16, v170
	v_and_b32_e32 v135, 0xffff0000, v170
	v_pk_mul_f32 v[130:131], v[130:131], v[134:135]
	v_lshl_add_u64 v[134:135], v[146:147], 0, v[0:1]
	v_pk_fma_f32 v[34:35], v[34:35], s[0:1], v[130:131] op_sel_hi:[1,0,1]
	v_lshlrev_b32_e32 v130, 16, v171
	v_and_b32_e32 v131, 0xffff0000, v171
	v_pk_mul_f32 v[130:131], v[132:133], v[130:131]
	v_add_f32_e32 v132, v42, v43
	v_pk_fma_f32 v[36:37], v[36:37], s[0:1], v[130:131] op_sel_hi:[1,0,1]
	v_add_f32_e32 v130, v48, v49
	v_add_f32_e32 v131, v46, v47
	v_add_f32_e32 v130, v131, v130
	v_add_f32_e32 v131, v44, v45
	v_add_f32_e32 v130, 0, v130
	v_add_f32_e32 v131, v132, v131
	v_add_f32_e32 v130, v130, v131
	v_add_f32_e32 v131, v40, v41
	v_add_f32_e32 v132, v38, v39
	v_add_f32_e32 v131, v132, v131
	v_add_f32_e32 v130, v130, v131
	v_add_f32_e32 v131, v36, v37
	v_add_f32_e32 v132, v34, v35
	v_add_f32_e32 v131, v132, v131
	v_add_f32_e32 v130, v130, v131
	v_add_f32_e32 v131, v100, v101
	v_add_f32_e32 v132, v98, v99
	v_add_f32_e32 v131, v132, v131
	v_add_f32_e32 v132, v96, v97
	v_add_f32_e32 v133, v94, v95
	v_add_f32_e32 v131, 0, v131
	v_add_f32_e32 v132, v133, v132
	v_add_f32_e32 v131, v131, v132
	v_add_f32_e32 v132, v88, v89
	v_add_f32_e32 v133, v86, v87
	v_add_f32_dpp v130, v130, v130 quad_perm:[1,0,3,2] row_mask:0xf bank_mask:0xf bound_ctrl:1
	v_add_f32_e32 v132, v133, v132
	v_add_f32_e32 v131, v131, v132
	v_add_f32_dpp v130, v130, v130 quad_perm:[2,3,0,1] row_mask:0xf bank_mask:0xf bound_ctrl:1
	v_add_f32_e32 v132, v84, v85
	v_add_f32_e32 v133, v82, v83
	v_add_f32_dpp v130, v130, v130 row_half_mirror row_mask:0xf bank_mask:0xf bound_ctrl:1
	v_add_f32_e32 v132, v133, v132
	v_add_f32_e32 v131, v131, v132
	v_add_f32_dpp v130, v130, v130 row_mirror row_mask:0xf bank_mask:0xf bound_ctrl:1
	v_mov_b32_e32 v132, v130
	s_nop 1
	v_permlane16_swap_b32_e32 v130, v132
	v_add_f32_dpp v131, v131, v131 quad_perm:[1,0,3,2] row_mask:0xf bank_mask:0xf bound_ctrl:1
	v_add_f32_e32 v130, v130, v132
	v_mov_b32_e32 v132, v130
	v_add_f32_dpp v131, v131, v131 quad_perm:[2,3,0,1] row_mask:0xf bank_mask:0xf bound_ctrl:1
	s_nop 0
	v_permlane32_swap_b32_e32 v130, v132
	v_add_f32_dpp v131, v131, v131 row_half_mirror row_mask:0xf bank_mask:0xf bound_ctrl:1
	v_add_f32_e32 v130, v130, v132
	v_mul_f32_e32 v130, 0x3a800000, v130
	v_add_f32_dpp v131, v131, v131 row_mirror row_mask:0xf bank_mask:0xf bound_ctrl:1
	v_mov_b32_e32 v132, v131
	s_nop 1
	v_permlane16_swap_b32_e32 v131, v132
	v_add_f32_e32 v131, v131, v132
	v_mov_b32_e32 v132, v131
	s_nop 1
	v_permlane32_swap_b32_e32 v131, v132
	v_add_f32_e32 v131, v131, v132
	v_pk_add_f32 v[46:47], v[46:47], v[130:131] op_sel_hi:[1,0] neg_lo:[0,1] neg_hi:[0,1]
	v_pk_add_f32 v[48:49], v[48:49], v[130:131] op_sel_hi:[1,0] neg_lo:[0,1] neg_hi:[0,1]
	v_pk_add_f32 v[42:43], v[42:43], v[130:131] op_sel_hi:[1,0] neg_lo:[0,1] neg_hi:[0,1]
	v_pk_add_f32 v[44:45], v[44:45], v[130:131] op_sel_hi:[1,0] neg_lo:[0,1] neg_hi:[0,1]
	v_pk_mul_f32 v[136:137], v[46:47], v[46:47]
	v_pk_mul_f32 v[138:139], v[48:49], v[48:49]
	v_pk_mul_f32 v[140:141], v[42:43], v[42:43]
	v_pk_mul_f32 v[142:143], v[44:45], v[44:45]
	v_pk_add_f32 v[144:145], v[38:39], v[130:131] op_sel_hi:[1,0] neg_lo:[0,1] neg_hi:[0,1]
	v_pk_add_f32 v[146:147], v[40:41], v[130:131] op_sel_hi:[1,0] neg_lo:[0,1] neg_hi:[0,1]
	v_mul_f32_e32 v132, 0x3a800000, v131
	v_pk_mul_f32 v[38:39], v[144:145], v[144:145]
	v_pk_mul_f32 v[40:41], v[146:147], v[146:147]
	v_pk_add_f32 v[148:149], v[34:35], v[130:131] op_sel_hi:[1,0] neg_lo:[0,1] neg_hi:[0,1]
	v_pk_add_f32 v[130:131], v[36:37], v[130:131] op_sel_hi:[1,0] neg_lo:[0,1] neg_hi:[0,1]
	v_add_f32_e32 v133, v142, v143
	v_add_f32_e32 v140, v140, v141
	v_add_f32_e32 v138, v138, v139
	v_add_f32_e32 v136, v136, v137
	v_pk_mul_f32 v[34:35], v[148:149], v[148:149]
	v_pk_mul_f32 v[36:37], v[130:131], v[130:131]
	v_add_f32_e32 v133, v140, v133
	v_add_f32_e32 v136, v136, v138
	v_add_f32_e32 v40, v40, v41
	v_add_f32_e32 v38, v38, v39
	v_add_f32_e32 v133, v136, v133
	v_add_f32_e32 v38, v38, v40
	v_add_f32_e32 v36, v36, v37
	v_add_f32_e32 v34, v34, v35
	v_add_f32_e32 v38, v38, v133
	v_add_f32_e32 v34, v34, v36
	v_add_f32_e32 v34, v34, v38
	v_pk_add_f32 v[94:95], v[94:95], v[132:133] op_sel_hi:[1,0] neg_lo:[0,1] neg_hi:[0,1]
	v_pk_add_f32 v[96:97], v[96:97], v[132:133] op_sel_hi:[1,0] neg_lo:[0,1] neg_hi:[0,1]
	v_add_f32_dpp v34, v34, v34 quad_perm:[1,0,3,2] row_mask:0xf bank_mask:0xf bound_ctrl:1
	v_pk_add_f32 v[98:99], v[98:99], v[132:133] op_sel_hi:[1,0] neg_lo:[0,1] neg_hi:[0,1]
	v_pk_add_f32 v[100:101], v[100:101], v[132:133] op_sel_hi:[1,0] neg_lo:[0,1] neg_hi:[0,1]
	v_add_f32_dpp v34, v34, v34 quad_perm:[2,3,0,1] row_mask:0xf bank_mask:0xf bound_ctrl:1
	v_pk_mul_f32 v[136:137], v[94:95], v[94:95]
	v_pk_mul_f32 v[138:139], v[96:97], v[96:97]
	v_add_f32_dpp v34, v34, v34 row_half_mirror row_mask:0xf bank_mask:0xf bound_ctrl:1
	v_pk_mul_f32 v[38:39], v[98:99], v[98:99]
	v_pk_mul_f32 v[40:41], v[100:101], v[100:101]
	v_add_f32_dpp v34, v34, v34 row_mirror row_mask:0xf bank_mask:0xf bound_ctrl:1
	v_mov_b32_e32 v35, v34
	s_nop 1
	v_permlane16_swap_b32_e32 v34, v35
	v_add_f32_e32 v35, v34, v35
	v_add_f32_e32 v34, v138, v139
	v_add_f32_e32 v36, v136, v137
	v_pk_add_f32 v[86:87], v[86:87], v[132:133] op_sel_hi:[1,0] neg_lo:[0,1] neg_hi:[0,1]
	v_pk_add_f32 v[88:89], v[88:89], v[132:133] op_sel_hi:[1,0] neg_lo:[0,1] neg_hi:[0,1]
	v_add_f32_e32 v34, v36, v34
	v_add_f32_e32 v36, v40, v41
	v_add_f32_e32 v38, v38, v39
	v_pk_mul_f32 v[140:141], v[86:87], v[86:87]
	v_pk_mul_f32 v[142:143], v[88:89], v[88:89]
	v_add_f32_e32 v36, v38, v36
	v_pk_add_f32 v[82:83], v[82:83], v[132:133] op_sel_hi:[1,0] neg_lo:[0,1] neg_hi:[0,1]
	v_pk_add_f32 v[84:85], v[84:85], v[132:133] op_sel_hi:[1,0] neg_lo:[0,1] neg_hi:[0,1]
	v_add_f32_e32 v34, v36, v34
	v_add_f32_e32 v36, v142, v143
	v_add_f32_e32 v38, v140, v141
	v_pk_mul_f32 v[150:151], v[82:83], v[82:83]
	v_pk_mul_f32 v[132:133], v[84:85], v[84:85]
	v_add_f32_e32 v36, v38, v36
	v_add_f32_e32 v34, v36, v34
	v_add_f32_e32 v36, v132, v133
	v_add_f32_e32 v38, v150, v151
	v_add_f32_e32 v36, v38, v36
	v_add_f32_e32 v34, v36, v34
	v_mov_b32_e32 v37, v35
	s_nop 1
	v_permlane32_swap_b32_e32 v35, v37
	v_add_f32_dpp v34, v34, v34 quad_perm:[1,0,3,2] row_mask:0xf bank_mask:0xf bound_ctrl:1
	s_mov_b32 s0, 0x3a800000
	v_lshl_add_u64 v[136:137], v[180:181], 0, v[0:1]
	v_add_f32_dpp v34, v34, v34 quad_perm:[2,3,0,1] row_mask:0xf bank_mask:0xf bound_ctrl:1
	s_mov_b32 s78, 0x800000
	s_waitcnt vmcnt(0)
	v_mov_b64_e32 v[182:183], v[208:209]
	v_add_f32_dpp v34, v34, v34 row_half_mirror row_mask:0xf bank_mask:0xf bound_ctrl:1
	v_mov_b64_e32 v[192:193], v[206:207]
	v_mov_b64_e32 v[194:195], v[204:205]
	v_add_f32_dpp v34, v34, v34 row_mirror row_mask:0xf bank_mask:0xf bound_ctrl:1
	v_mov_b32_e32 v36, v34
	s_nop 1
	v_permlane16_swap_b32_e32 v34, v36
	v_add_f32_e32 v34, v34, v36
	v_mov_b32_e32 v36, v34
	s_nop 1
	v_permlane32_swap_b32_e32 v34, v36
	v_pk_add_f32 v[34:35], v[34:35], v[36:37]
	v_mov_b64_e32 v[196:197], v[200:201]
	v_pk_fma_f32 v[132:133], v[34:35], s[0:1], v[162:163] op_sel_hi:[1,0,0]
	s_mov_b32 s0, 0x800000
	v_mul_f32_e32 v34, 0x4b800000, v133
	v_cmp_gt_f32_e32 vcc, s0, v133
	v_mov_b64_e32 v[170:171], v[190:191]
	v_mov_b64_e32 v[172:173], v[188:189]
	v_cndmask_b32_e32 v34, v133, v34, vcc
	v_rsq_f32_e32 v34, v34
	v_mov_b64_e32 v[174:175], v[186:187]
	v_mov_b64_e32 v[176:177], v[184:185]
	v_mov_b32_e32 v180, v178
	v_mul_f32_e32 v35, 0x45800000, v34
	v_cndmask_b32_e32 v138, v34, v35, vcc
	v_pk_mul_f32 v[34:35], v[46:47], v[138:139] op_sel_hi:[1,0]
	v_pk_mul_f32 v[36:37], v[48:49], v[138:139] op_sel_hi:[1,0]
	v_pk_fma_f32 v[34:35], v[2:3], v[34:35], v[10:11]
	v_pk_fma_f32 v[36:37], v[4:5], v[36:37], v[12:13]
	v_pk_mul_f32 v[38:39], v[42:43], v[138:139] op_sel_hi:[1,0]
	v_pk_mul_f32 v[40:41], v[44:45], v[138:139] op_sel_hi:[1,0]
	v_pk_mul_f32 v[42:43], v[144:145], v[138:139] op_sel_hi:[1,0]
	v_pk_mul_f32 v[44:45], v[146:147], v[138:139] op_sel_hi:[1,0]
	v_pk_mul_f32 v[46:47], v[148:149], v[138:139] op_sel_hi:[1,0]
	v_pk_mul_f32 v[48:49], v[130:131], v[138:139] op_sel_hi:[1,0]
	v_pk_fma_f32 v[38:39], v[6:7], v[38:39], v[14:15]
	v_pk_fma_f32 v[40:41], v[8:9], v[40:41], v[16:17]
	v_pk_fma_f32 v[42:43], v[18:19], v[42:43], v[26:27]
	v_pk_fma_f32 v[44:45], v[20:21], v[44:45], v[28:29]
	v_pk_fma_f32 v[46:47], v[22:23], v[46:47], v[30:31]
	v_pk_fma_f32 v[48:49], v[24:25], v[48:49], v[32:33]
	global_store_dwordx4 v[134:135], v[34:37], off nt
	global_store_dwordx4 v[134:135], v[38:41], off offset:1024 nt
	global_store_dwordx4 v[134:135], v[42:45], off offset:2048 nt
	global_store_dwordx4 v[134:135], v[46:49], off offset:3072 nt
	v_pk_fma_f32 v[34:35], v[126:127], v[34:35], v[62:63]
	v_pk_fma_f32 v[36:37], v[128:129], v[36:37], v[64:65]
	v_cvt_pk_bf16_f32 v34, v34, v35
	v_cvt_pk_bf16_f32 v35, v36, v37
	global_store_dwordx2 v[168:169], v[34:35], off offset:-2048 nt
	v_pk_fma_f32 v[34:35], v[118:119], v[38:39], v[58:59]
	v_pk_fma_f32 v[36:37], v[120:121], v[40:41], v[60:61]
	v_cvt_pk_bf16_f32 v34, v34, v35
	v_cvt_pk_bf16_f32 v35, v36, v37
	global_store_dwordx2 v[168:169], v[34:35], off offset:-1536 nt
	v_pk_fma_f32 v[34:35], v[122:123], v[42:43], v[54:55]
	v_pk_fma_f32 v[36:37], v[124:125], v[44:45], v[56:57]
	v_cvt_pk_bf16_f32 v34, v34, v35
	v_cvt_pk_bf16_f32 v35, v36, v37
	global_store_dwordx2 v[168:169], v[34:35], off offset:-1024 nt
	v_pk_fma_f32 v[34:35], v[90:91], v[46:47], v[50:51]
	v_cmp_gt_f32_e32 vcc, s0, v132
	v_cvt_pk_bf16_f32 v34, v34, v35
	v_mul_f32_e32 v35, 0x4b800000, v132
	v_cndmask_b32_e32 v35, v132, v35, vcc
	v_rsq_f32_e32 v38, v35
	v_pk_fma_f32 v[36:37], v[92:93], v[48:49], v[52:53]
	v_readlane_b32 s0, v244, 31
	v_cvt_pk_bf16_f32 v35, v36, v37
	global_store_dwordx2 v[168:169], v[34:35], off offset:-512 nt
	v_mul_f32_e32 v34, 0x45800000, v38
	v_cndmask_b32_e32 v48, v38, v34, vcc
	v_pk_mul_f32 v[34:35], v[98:99], v[48:49] op_sel_hi:[1,0]
	v_pk_mul_f32 v[36:37], v[100:101], v[48:49] op_sel_hi:[1,0]
	v_pk_fma_f32 v[34:35], v[2:3], v[34:35], v[10:11]
	v_pk_fma_f32 v[36:37], v[4:5], v[36:37], v[12:13]
	v_pk_mul_f32 v[38:39], v[94:95], v[48:49] op_sel_hi:[1,0]
	v_pk_mul_f32 v[40:41], v[96:97], v[48:49] op_sel_hi:[1,0]
	v_pk_mul_f32 v[42:43], v[86:87], v[48:49] op_sel_hi:[1,0]
	v_pk_mul_f32 v[44:45], v[88:89], v[48:49] op_sel_hi:[1,0]
	v_pk_mul_f32 v[46:47], v[82:83], v[48:49] op_sel_hi:[1,0]
	v_pk_mul_f32 v[48:49], v[84:85], v[48:49] op_sel_hi:[1,0]
	v_pk_fma_f32 v[38:39], v[6:7], v[38:39], v[14:15]
	v_pk_fma_f32 v[40:41], v[8:9], v[40:41], v[16:17]
	v_pk_fma_f32 v[42:43], v[18:19], v[42:43], v[26:27]
	v_pk_fma_f32 v[44:45], v[20:21], v[44:45], v[28:29]
	v_pk_fma_f32 v[46:47], v[22:23], v[46:47], v[30:31]
	v_pk_fma_f32 v[48:49], v[24:25], v[48:49], v[32:33]
	global_store_dwordx4 v[136:137], v[34:37], off nt
	global_store_dwordx4 v[136:137], v[38:41], off offset:1024 nt
	global_store_dwordx4 v[136:137], v[42:45], off offset:2048 nt
	global_store_dwordx4 v[136:137], v[46:49], off offset:3072 nt
	v_pk_fma_f32 v[34:35], v[126:127], v[34:35], v[62:63]
	v_pk_fma_f32 v[36:37], v[128:129], v[36:37], v[64:65]
	v_cvt_pk_bf16_f32 v34, v34, v35
	v_cvt_pk_bf16_f32 v35, v36, v37
	global_store_dwordx2 v[168:169], v[34:35], off nt
	v_pk_fma_f32 v[34:35], v[118:119], v[38:39], v[58:59]
	v_pk_fma_f32 v[36:37], v[120:121], v[40:41], v[60:61]
	v_cvt_pk_bf16_f32 v34, v34, v35
	v_cvt_pk_bf16_f32 v35, v36, v37
	global_store_dwordx2 v[168:169], v[34:35], off offset:512 nt
	v_pk_fma_f32 v[34:35], v[122:123], v[42:43], v[54:55]
	v_pk_fma_f32 v[36:37], v[124:125], v[44:45], v[56:57]
	v_cvt_pk_bf16_f32 v34, v34, v35
	v_cvt_pk_bf16_f32 v35, v36, v37
	global_store_dwordx2 v[168:169], v[34:35], off offset:1024 nt
	v_pk_fma_f32 v[34:35], v[90:91], v[46:47], v[50:51]
	v_pk_fma_f32 v[36:37], v[92:93], v[48:49], v[52:53]
	v_cvt_pk_bf16_f32 v34, v34, v35
	v_cvt_pk_bf16_f32 v35, v36, v37
	v_readlane_b32 s1, v244, 32
	global_store_dwordx2 v[168:169], v[34:35], off offset:1536 nt
	v_mov_b64_e32 v[46:47], v[78:79]
	v_lshl_add_u64 v[168:169], v[168:169], 0, s[0:1]
	v_mov_b64_e32 v[48:49], v[80:81]
	v_mov_b64_e32 v[42:43], v[74:75]
	v_mov_b64_e32 v[44:45], v[76:77]
	v_mov_b64_e32 v[38:39], v[70:71]
	v_mov_b64_e32 v[40:41], v[72:73]
	v_mov_b64_e32 v[34:35], v[66:67]
	v_mov_b64_e32 v[36:37], v[68:69]
	v_mov_b64_e32 v[98:99], v[102:103]
	v_mov_b64_e32 v[100:101], v[104:105]
	v_mov_b64_e32 v[94:95], v[106:107]
	v_mov_b64_e32 v[96:97], v[108:109]
	v_mov_b64_e32 v[86:87], v[110:111]
	v_mov_b64_e32 v[88:89], v[112:113]
	v_mov_b64_e32 v[82:83], v[114:115]
	v_mov_b64_e32 v[84:85], v[116:117]
	s_andn2_b64 exec, exec, s[6:7]
	s_cbranch_execz .LBB0_179

.LBB0_737:
	s_or_b64 exec, exec, s[30:31]
	s_and_b64 s[0:1], exec, vcc
	v_lshlrev_b64 v[180:181], 12, v[210:211]
	v_lshlrev_b32_e32 v210, 16, v196
	v_and_b32_e32 v211, 0xffff0000, v196
	s_or_b64 s[6:7], s[0:1], s[6:7]
	v_pk_mul_f32 v[158:159], v[158:159], v[210:211]
	s_mov_b32 s0, 0x3fd744fd
	v_pk_fma_f32 v[98:99], v[98:99], s[0:1], v[158:159] op_sel_hi:[1,0,1]
	v_lshlrev_b32_e32 v158, 16, v197
	v_and_b32_e32 v159, 0xffff0000, v197
	v_pk_mul_f32 v[158:159], v[160:161], v[158:159]
	v_pk_add_f32 v[126:127], v[126:127], 1.0 op_sel_hi:[1,0]
	v_pk_fma_f32 v[100:101], v[100:101], s[0:1], v[158:159] op_sel_hi:[1,0,1]
	v_lshlrev_b32_e32 v158, 16, v194
	v_and_b32_e32 v159, 0xffff0000, v194
	v_pk_mul_f32 v[154:155], v[154:155], v[158:159]
	v_pk_add_f32 v[128:129], v[128:129], 1.0 op_sel_hi:[1,0]
	v_pk_fma_f32 v[94:95], v[94:95], s[0:1], v[154:155] op_sel_hi:[1,0,1]
	v_lshlrev_b32_e32 v154, 16, v195
	v_and_b32_e32 v155, 0xffff0000, v195
	v_pk_mul_f32 v[154:155], v[156:157], v[154:155]
	v_pk_add_f32 v[118:119], v[118:119], 1.0 op_sel_hi:[1,0]
	v_pk_fma_f32 v[96:97], v[96:97], s[0:1], v[154:155] op_sel_hi:[1,0,1]
	v_lshlrev_b32_e32 v154, 16, v192
	v_and_b32_e32 v155, 0xffff0000, v192
	v_pk_mul_f32 v[150:151], v[150:151], v[154:155]
	v_pk_add_f32 v[120:121], v[120:121], 1.0 op_sel_hi:[1,0]
	v_pk_fma_f32 v[86:87], v[86:87], s[0:1], v[150:151] op_sel_hi:[1,0,1]
	v_lshlrev_b32_e32 v150, 16, v193
	v_and_b32_e32 v151, 0xffff0000, v193
	v_pk_mul_f32 v[150:151], v[152:153], v[150:151]
	v_pk_add_f32 v[122:123], v[122:123], 1.0 op_sel_hi:[1,0]
	v_pk_fma_f32 v[88:89], v[88:89], s[0:1], v[150:151] op_sel_hi:[1,0,1]
	v_lshlrev_b32_e32 v150, 16, v184
	v_and_b32_e32 v151, 0xffff0000, v184
	v_pk_mul_f32 v[146:147], v[146:147], v[150:151]
	v_pk_add_f32 v[124:125], v[124:125], 1.0 op_sel_hi:[1,0]
	v_pk_fma_f32 v[82:83], v[82:83], s[0:1], v[146:147] op_sel_hi:[1,0,1]
	v_lshlrev_b32_e32 v146, 16, v185
	v_and_b32_e32 v147, 0xffff0000, v185
	v_pk_mul_f32 v[146:147], v[148:149], v[146:147]
	v_lshlrev_b32_e32 v148, 16, v176
	v_and_b32_e32 v149, 0xffff0000, v176
	v_pk_mul_f32 v[142:143], v[142:143], v[148:149]
	v_pk_fma_f32 v[84:85], v[84:85], s[0:1], v[146:147] op_sel_hi:[1,0,1]
	v_pk_fma_f32 v[46:47], v[46:47], s[0:1], v[142:143] op_sel_hi:[1,0,1]
	v_lshlrev_b32_e32 v142, 16, v177
	v_and_b32_e32 v143, 0xffff0000, v177
	v_pk_mul_f32 v[142:143], v[144:145], v[142:143]
	v_lshlrev_b64 v[146:147], 12, v[198:199]
	v_pk_fma_f32 v[48:49], v[48:49], s[0:1], v[142:143] op_sel_hi:[1,0,1]
	v_lshlrev_b32_e32 v142, 16, v174
	v_and_b32_e32 v143, 0xffff0000, v174
	v_pk_mul_f32 v[138:139], v[138:139], v[142:143]
	v_lshl_add_u64 v[146:147], v[202:203], 0, v[146:147]
	v_pk_fma_f32 v[42:43], v[42:43], s[0:1], v[138:139] op_sel_hi:[1,0,1]
	v_lshlrev_b32_e32 v138, 16, v175
	v_and_b32_e32 v139, 0xffff0000, v175
	v_pk_mul_f32 v[138:139], v[140:141], v[138:139]
	v_pk_add_f32 v[90:91], v[90:91], 1.0 op_sel_hi:[1,0]
	v_pk_fma_f32 v[44:45], v[44:45], s[0:1], v[138:139] op_sel_hi:[1,0,1]
	v_lshlrev_b32_e32 v138, 16, v172
	v_and_b32_e32 v139, 0xffff0000, v172
	v_pk_mul_f32 v[134:135], v[134:135], v[138:139]
	v_pk_add_f32 v[92:93], v[92:93], 1.0 op_sel_hi:[1,0]
	v_pk_fma_f32 v[38:39], v[38:39], s[0:1], v[134:135] op_sel_hi:[1,0,1]
	v_lshlrev_b32_e32 v134, 16, v173
	v_and_b32_e32 v135, 0xffff0000, v173
	v_pk_mul_f32 v[134:135], v[136:137], v[134:135]
	v_lshl_add_u64 v[180:181], v[212:213], 0, v[180:181]
	v_pk_fma_f32 v[40:41], v[40:41], s[0:1], v[134:135] op_sel_hi:[1,0,1]
	v_lshlrev_b32_e32 v134, 16, v170
	v_and_b32_e32 v135, 0xffff0000, v170
	v_pk_mul_f32 v[130:131], v[130:131], v[134:135]
	v_lshl_add_u64 v[134:135], v[146:147], 0, v[0:1]
	v_pk_fma_f32 v[34:35], v[34:35], s[0:1], v[130:131] op_sel_hi:[1,0,1]
	v_lshlrev_b32_e32 v130, 16, v171
	v_and_b32_e32 v131, 0xffff0000, v171
	v_pk_mul_f32 v[130:131], v[132:133], v[130:131]
	v_add_f32_e32 v132, v42, v43
	v_pk_fma_f32 v[36:37], v[36:37], s[0:1], v[130:131] op_sel_hi:[1,0,1]
	v_add_f32_e32 v130, v48, v49
	v_add_f32_e32 v131, v46, v47
	v_add_f32_e32 v130, v131, v130
	v_add_f32_e32 v131, v44, v45
	v_add_f32_e32 v130, 0, v130
	v_add_f32_e32 v131, v132, v131
	v_add_f32_e32 v130, v130, v131
	v_add_f32_e32 v131, v40, v41
	v_add_f32_e32 v132, v38, v39
	v_add_f32_e32 v131, v132, v131
	v_add_f32_e32 v130, v130, v131
	v_add_f32_e32 v131, v36, v37
	v_add_f32_e32 v132, v34, v35
	v_add_f32_e32 v131, v132, v131
	v_add_f32_e32 v130, v130, v131
	v_add_f32_e32 v131, v100, v101
	v_add_f32_e32 v132, v98, v99
	v_add_f32_e32 v131, v132, v131
	v_add_f32_e32 v132, v96, v97
	v_add_f32_e32 v133, v94, v95
	v_add_f32_e32 v131, 0, v131
	v_add_f32_e32 v132, v133, v132
	v_add_f32_e32 v131, v131, v132
	v_add_f32_e32 v132, v88, v89
	v_add_f32_e32 v133, v86, v87
	v_add_f32_dpp v130, v130, v130 quad_perm:[1,0,3,2] row_mask:0xf bank_mask:0xf bound_ctrl:1
	v_add_f32_e32 v132, v133, v132
	v_add_f32_e32 v131, v131, v132
	v_add_f32_dpp v130, v130, v130 quad_perm:[2,3,0,1] row_mask:0xf bank_mask:0xf bound_ctrl:1
	v_add_f32_e32 v132, v84, v85
	v_add_f32_e32 v133, v82, v83
	v_add_f32_dpp v130, v130, v130 row_half_mirror row_mask:0xf bank_mask:0xf bound_ctrl:1
	v_add_f32_e32 v132, v133, v132
	v_add_f32_e32 v131, v131, v132
	v_add_f32_dpp v130, v130, v130 row_mirror row_mask:0xf bank_mask:0xf bound_ctrl:1
	v_mov_b32_e32 v132, v130
	s_nop 1
	v_permlane16_swap_b32_e32 v130, v132
	v_add_f32_dpp v131, v131, v131 quad_perm:[1,0,3,2] row_mask:0xf bank_mask:0xf bound_ctrl:1
	v_add_f32_e32 v130, v130, v132
	v_mov_b32_e32 v132, v130
	v_add_f32_dpp v131, v131, v131 quad_perm:[2,3,0,1] row_mask:0xf bank_mask:0xf bound_ctrl:1
	s_nop 0
	v_permlane32_swap_b32_e32 v130, v132
	v_add_f32_dpp v131, v131, v131 row_half_mirror row_mask:0xf bank_mask:0xf bound_ctrl:1
	v_add_f32_e32 v130, v130, v132
	v_mul_f32_e32 v130, 0x3a800000, v130
	v_add_f32_dpp v131, v131, v131 row_mirror row_mask:0xf bank_mask:0xf bound_ctrl:1
	v_mov_b32_e32 v132, v131
	s_nop 1
	v_permlane16_swap_b32_e32 v131, v132
	v_add_f32_e32 v131, v131, v132
	v_mov_b32_e32 v132, v131
	s_nop 1
	v_permlane32_swap_b32_e32 v131, v132
	v_add_f32_e32 v131, v131, v132
	v_pk_add_f32 v[46:47], v[46:47], v[130:131] op_sel_hi:[1,0] neg_lo:[0,1] neg_hi:[0,1]
	v_pk_add_f32 v[48:49], v[48:49], v[130:131] op_sel_hi:[1,0] neg_lo:[0,1] neg_hi:[0,1]
	v_pk_add_f32 v[42:43], v[42:43], v[130:131] op_sel_hi:[1,0] neg_lo:[0,1] neg_hi:[0,1]
	v_pk_add_f32 v[44:45], v[44:45], v[130:131] op_sel_hi:[1,0] neg_lo:[0,1] neg_hi:[0,1]
	v_pk_mul_f32 v[136:137], v[46:47], v[46:47]
	v_pk_mul_f32 v[138:139], v[48:49], v[48:49]
	v_pk_mul_f32 v[140:141], v[42:43], v[42:43]
	v_pk_mul_f32 v[142:143], v[44:45], v[44:45]
	v_pk_add_f32 v[144:145], v[38:39], v[130:131] op_sel_hi:[1,0] neg_lo:[0,1] neg_hi:[0,1]
	v_pk_add_f32 v[146:147], v[40:41], v[130:131] op_sel_hi:[1,0] neg_lo:[0,1] neg_hi:[0,1]
	v_mul_f32_e32 v132, 0x3a800000, v131
	v_pk_mul_f32 v[38:39], v[144:145], v[144:145]
	v_pk_mul_f32 v[40:41], v[146:147], v[146:147]
	v_pk_add_f32 v[148:149], v[34:35], v[130:131] op_sel_hi:[1,0] neg_lo:[0,1] neg_hi:[0,1]
	v_pk_add_f32 v[130:131], v[36:37], v[130:131] op_sel_hi:[1,0] neg_lo:[0,1] neg_hi:[0,1]
	v_add_f32_e32 v133, v142, v143
	v_add_f32_e32 v140, v140, v141
	v_add_f32_e32 v138, v138, v139
	v_add_f32_e32 v136, v136, v137
	v_pk_mul_f32 v[34:35], v[148:149], v[148:149]
	v_pk_mul_f32 v[36:37], v[130:131], v[130:131]
	v_add_f32_e32 v133, v140, v133
	v_add_f32_e32 v136, v136, v138
	v_add_f32_e32 v40, v40, v41
	v_add_f32_e32 v38, v38, v39
	v_add_f32_e32 v133, v136, v133
	v_add_f32_e32 v38, v38, v40
	v_add_f32_e32 v36, v36, v37
	v_add_f32_e32 v34, v34, v35
	v_add_f32_e32 v38, v38, v133
	v_add_f32_e32 v34, v34, v36
	v_add_f32_e32 v34, v34, v38
	v_pk_add_f32 v[94:95], v[94:95], v[132:133] op_sel_hi:[1,0] neg_lo:[0,1] neg_hi:[0,1]
	v_pk_add_f32 v[96:97], v[96:97], v[132:133] op_sel_hi:[1,0] neg_lo:[0,1] neg_hi:[0,1]
	v_add_f32_dpp v34, v34, v34 quad_perm:[1,0,3,2] row_mask:0xf bank_mask:0xf bound_ctrl:1
	v_pk_add_f32 v[98:99], v[98:99], v[132:133] op_sel_hi:[1,0] neg_lo:[0,1] neg_hi:[0,1]
	v_pk_add_f32 v[100:101], v[100:101], v[132:133] op_sel_hi:[1,0] neg_lo:[0,1] neg_hi:[0,1]
	v_add_f32_dpp v34, v34, v34 quad_perm:[2,3,0,1] row_mask:0xf bank_mask:0xf bound_ctrl:1
	v_pk_mul_f32 v[136:137], v[94:95], v[94:95]
	v_pk_mul_f32 v[138:139], v[96:97], v[96:97]
	v_add_f32_dpp v34, v34, v34 row_half_mirror row_mask:0xf bank_mask:0xf bound_ctrl:1
	v_pk_mul_f32 v[38:39], v[98:99], v[98:99]
	v_pk_mul_f32 v[40:41], v[100:101], v[100:101]
	v_add_f32_dpp v34, v34, v34 row_mirror row_mask:0xf bank_mask:0xf bound_ctrl:1
	v_mov_b32_e32 v35, v34
	s_nop 1
	v_permlane16_swap_b32_e32 v34, v35
	v_add_f32_e32 v35, v34, v35
	v_add_f32_e32 v34, v138, v139
	v_add_f32_e32 v36, v136, v137
	v_pk_add_f32 v[86:87], v[86:87], v[132:133] op_sel_hi:[1,0] neg_lo:[0,1] neg_hi:[0,1]
	v_pk_add_f32 v[88:89], v[88:89], v[132:133] op_sel_hi:[1,0] neg_lo:[0,1] neg_hi:[0,1]
	v_add_f32_e32 v34, v36, v34
	v_add_f32_e32 v36, v40, v41
	v_add_f32_e32 v38, v38, v39
	v_pk_mul_f32 v[140:141], v[86:87], v[86:87]
	v_pk_mul_f32 v[142:143], v[88:89], v[88:89]
	v_add_f32_e32 v36, v38, v36
	v_pk_add_f32 v[82:83], v[82:83], v[132:133] op_sel_hi:[1,0] neg_lo:[0,1] neg_hi:[0,1]
	v_pk_add_f32 v[84:85], v[84:85], v[132:133] op_sel_hi:[1,0] neg_lo:[0,1] neg_hi:[0,1]
	v_add_f32_e32 v34, v36, v34
	v_add_f32_e32 v36, v142, v143
	v_add_f32_e32 v38, v140, v141
	v_pk_mul_f32 v[150:151], v[82:83], v[82:83]
	v_pk_mul_f32 v[132:133], v[84:85], v[84:85]
	v_add_f32_e32 v36, v38, v36
	v_add_f32_e32 v34, v36, v34
	v_add_f32_e32 v36, v132, v133
	v_add_f32_e32 v38, v150, v151
	v_add_f32_e32 v36, v38, v36
	v_add_f32_e32 v34, v36, v34
	v_mov_b32_e32 v37, v35
	s_nop 1
	v_permlane32_swap_b32_e32 v35, v37
	v_add_f32_dpp v34, v34, v34 quad_perm:[1,0,3,2] row_mask:0xf bank_mask:0xf bound_ctrl:1
	s_mov_b32 s0, 0x3a800000
	v_lshl_add_u64 v[136:137], v[180:181], 0, v[0:1]
	v_add_f32_dpp v34, v34, v34 quad_perm:[2,3,0,1] row_mask:0xf bank_mask:0xf bound_ctrl:1
	s_mov_b32 s78, 0x800000
	s_waitcnt vmcnt(0)
	v_mov_b64_e32 v[184:185], v[208:209]
	v_add_f32_dpp v34, v34, v34 row_half_mirror row_mask:0xf bank_mask:0xf bound_ctrl:1
	v_mov_b64_e32 v[192:193], v[206:207]
	v_mov_b64_e32 v[194:195], v[204:205]
	v_add_f32_dpp v34, v34, v34 row_mirror row_mask:0xf bank_mask:0xf bound_ctrl:1
	v_mov_b32_e32 v36, v34
	s_nop 1
	v_permlane16_swap_b32_e32 v34, v36
	v_add_f32_e32 v34, v34, v36
	v_mov_b32_e32 v36, v34
	s_nop 1
	v_permlane32_swap_b32_e32 v34, v36
	v_pk_add_f32 v[34:35], v[34:35], v[36:37]
	v_mov_b64_e32 v[196:197], v[200:201]
	v_pk_fma_f32 v[132:133], v[34:35], s[0:1], v[162:163] op_sel_hi:[1,0,0]
	s_mov_b32 s0, 0x800000
	v_mul_f32_e32 v34, 0x4b800000, v133
	v_cmp_gt_f32_e32 vcc, s0, v133
	v_mov_b64_e32 v[170:171], v[190:191]
	v_mov_b64_e32 v[172:173], v[188:189]
	v_cndmask_b32_e32 v34, v133, v34, vcc
	v_rsq_f32_e32 v34, v34
	v_mov_b64_e32 v[174:175], v[186:187]
	v_mov_b64_e32 v[176:177], v[182:183]
	v_mov_b32_e32 v180, v178
	v_mul_f32_e32 v35, 0x45800000, v34
	v_cndmask_b32_e32 v138, v34, v35, vcc
	v_pk_mul_f32 v[34:35], v[46:47], v[138:139] op_sel_hi:[1,0]
	v_pk_mul_f32 v[36:37], v[48:49], v[138:139] op_sel_hi:[1,0]
	v_pk_fma_f32 v[34:35], v[2:3], v[34:35], v[10:11]
	v_pk_fma_f32 v[36:37], v[4:5], v[36:37], v[12:13]
	v_pk_mul_f32 v[38:39], v[42:43], v[138:139] op_sel_hi:[1,0]
	v_pk_mul_f32 v[40:41], v[44:45], v[138:139] op_sel_hi:[1,0]
	v_pk_mul_f32 v[42:43], v[144:145], v[138:139] op_sel_hi:[1,0]
	v_pk_mul_f32 v[44:45], v[146:147], v[138:139] op_sel_hi:[1,0]
	v_pk_mul_f32 v[46:47], v[148:149], v[138:139] op_sel_hi:[1,0]
	v_pk_mul_f32 v[48:49], v[130:131], v[138:139] op_sel_hi:[1,0]
	v_pk_fma_f32 v[38:39], v[6:7], v[38:39], v[14:15]
	v_pk_fma_f32 v[40:41], v[8:9], v[40:41], v[16:17]
	v_pk_fma_f32 v[42:43], v[18:19], v[42:43], v[26:27]
	v_pk_fma_f32 v[44:45], v[20:21], v[44:45], v[28:29]
	v_pk_fma_f32 v[46:47], v[22:23], v[46:47], v[30:31]
	v_pk_fma_f32 v[48:49], v[24:25], v[48:49], v[32:33]
	global_store_dwordx4 v[134:135], v[34:37], off nt
	global_store_dwordx4 v[134:135], v[38:41], off offset:1024 nt
	global_store_dwordx4 v[134:135], v[42:45], off offset:2048 nt
	global_store_dwordx4 v[134:135], v[46:49], off offset:3072 nt
	v_pk_fma_f32 v[34:35], v[126:127], v[34:35], v[62:63]
	v_pk_fma_f32 v[36:37], v[128:129], v[36:37], v[64:65]
	v_cvt_pk_bf16_f32 v34, v34, v35
	v_cvt_pk_bf16_f32 v35, v36, v37
	global_store_dwordx2 v[168:169], v[34:35], off offset:-2048 nt
	v_pk_fma_f32 v[34:35], v[118:119], v[38:39], v[58:59]
	v_pk_fma_f32 v[36:37], v[120:121], v[40:41], v[60:61]
	v_cvt_pk_bf16_f32 v34, v34, v35
	v_cvt_pk_bf16_f32 v35, v36, v37
	global_store_dwordx2 v[168:169], v[34:35], off offset:-1536 nt
	v_pk_fma_f32 v[34:35], v[122:123], v[42:43], v[54:55]
	v_pk_fma_f32 v[36:37], v[124:125], v[44:45], v[56:57]
	v_cvt_pk_bf16_f32 v34, v34, v35
	v_cvt_pk_bf16_f32 v35, v36, v37
	global_store_dwordx2 v[168:169], v[34:35], off offset:-1024 nt
	v_pk_fma_f32 v[34:35], v[90:91], v[46:47], v[50:51]
	v_cmp_gt_f32_e32 vcc, s0, v132
	v_cvt_pk_bf16_f32 v34, v34, v35
	v_mul_f32_e32 v35, 0x4b800000, v132
	v_cndmask_b32_e32 v35, v132, v35, vcc
	v_rsq_f32_e32 v38, v35
	v_pk_fma_f32 v[36:37], v[92:93], v[48:49], v[52:53]
	v_readlane_b32 s0, v244, 31
	v_cvt_pk_bf16_f32 v35, v36, v37
	global_store_dwordx2 v[168:169], v[34:35], off offset:-512 nt
	v_mul_f32_e32 v34, 0x45800000, v38
	v_cndmask_b32_e32 v48, v38, v34, vcc
	v_pk_mul_f32 v[34:35], v[98:99], v[48:49] op_sel_hi:[1,0]
	v_pk_mul_f32 v[36:37], v[100:101], v[48:49] op_sel_hi:[1,0]
	v_pk_fma_f32 v[34:35], v[2:3], v[34:35], v[10:11]
	v_pk_fma_f32 v[36:37], v[4:5], v[36:37], v[12:13]
	v_pk_mul_f32 v[38:39], v[94:95], v[48:49] op_sel_hi:[1,0]
	v_pk_mul_f32 v[40:41], v[96:97], v[48:49] op_sel_hi:[1,0]
	v_pk_mul_f32 v[42:43], v[86:87], v[48:49] op_sel_hi:[1,0]
	v_pk_mul_f32 v[44:45], v[88:89], v[48:49] op_sel_hi:[1,0]
	v_pk_mul_f32 v[46:47], v[82:83], v[48:49] op_sel_hi:[1,0]
	v_pk_mul_f32 v[48:49], v[84:85], v[48:49] op_sel_hi:[1,0]
	v_pk_fma_f32 v[38:39], v[6:7], v[38:39], v[14:15]
	v_pk_fma_f32 v[40:41], v[8:9], v[40:41], v[16:17]
	v_pk_fma_f32 v[42:43], v[18:19], v[42:43], v[26:27]
	v_pk_fma_f32 v[44:45], v[20:21], v[44:45], v[28:29]
	v_pk_fma_f32 v[46:47], v[22:23], v[46:47], v[30:31]
	v_pk_fma_f32 v[48:49], v[24:25], v[48:49], v[32:33]
	global_store_dwordx4 v[136:137], v[34:37], off nt
	global_store_dwordx4 v[136:137], v[38:41], off offset:1024 nt
	global_store_dwordx4 v[136:137], v[42:45], off offset:2048 nt
	global_store_dwordx4 v[136:137], v[46:49], off offset:3072 nt
	v_pk_fma_f32 v[34:35], v[126:127], v[34:35], v[62:63]
	v_pk_fma_f32 v[36:37], v[128:129], v[36:37], v[64:65]
	v_cvt_pk_bf16_f32 v34, v34, v35
	v_cvt_pk_bf16_f32 v35, v36, v37
	global_store_dwordx2 v[168:169], v[34:35], off nt
	v_pk_fma_f32 v[34:35], v[118:119], v[38:39], v[58:59]
	v_pk_fma_f32 v[36:37], v[120:121], v[40:41], v[60:61]
	v_cvt_pk_bf16_f32 v34, v34, v35
	v_cvt_pk_bf16_f32 v35, v36, v37
	global_store_dwordx2 v[168:169], v[34:35], off offset:512 nt
	v_pk_fma_f32 v[34:35], v[122:123], v[42:43], v[54:55]
	v_pk_fma_f32 v[36:37], v[124:125], v[44:45], v[56:57]
	v_cvt_pk_bf16_f32 v34, v34, v35
	v_cvt_pk_bf16_f32 v35, v36, v37
	global_store_dwordx2 v[168:169], v[34:35], off offset:1024 nt
	v_pk_fma_f32 v[34:35], v[90:91], v[46:47], v[50:51]
	v_pk_fma_f32 v[36:37], v[92:93], v[48:49], v[52:53]
	v_cvt_pk_bf16_f32 v34, v34, v35
	v_cvt_pk_bf16_f32 v35, v36, v37
	v_readlane_b32 s1, v244, 32
	global_store_dwordx2 v[168:169], v[34:35], off offset:1536 nt
	v_mov_b64_e32 v[46:47], v[78:79]
	v_lshl_add_u64 v[168:169], v[168:169], 0, s[0:1]
	v_mov_b64_e32 v[48:49], v[80:81]
	v_mov_b64_e32 v[42:43], v[74:75]
	v_mov_b64_e32 v[44:45], v[76:77]
	v_mov_b64_e32 v[38:39], v[70:71]
	v_mov_b64_e32 v[40:41], v[72:73]
	v_mov_b64_e32 v[34:35], v[66:67]
	v_mov_b64_e32 v[36:37], v[68:69]
	v_mov_b64_e32 v[98:99], v[102:103]
	v_mov_b64_e32 v[100:101], v[104:105]
	v_mov_b64_e32 v[94:95], v[106:107]
	v_mov_b64_e32 v[96:97], v[108:109]
	v_mov_b64_e32 v[86:87], v[110:111]
	v_mov_b64_e32 v[88:89], v[112:113]
	v_mov_b64_e32 v[82:83], v[114:115]
	v_mov_b64_e32 v[84:85], v[116:117]
	s_andn2_b64 exec, exec, s[6:7]
	s_cbranch_execz .LBB0_755

.LBB0_767:
	s_or_b64 exec, exec, s[30:31]
	v_lshlrev_b64 v[102:103], 12, v[102:103]
	v_lshl_add_u64 v[102:103], v[104:105], 0, v[102:103]
	v_lshl_add_u64 v[102:103], v[102:103], 0, v[0:1]
	v_pk_add_f32 v[78:79], v[78:79], 1.0 op_sel_hi:[1,0]
	v_pk_add_f32 v[80:81], v[80:81], 1.0 op_sel_hi:[1,0]
	global_store_dwordx4 v[102:103], v[14:17], off nt
	global_store_dwordx4 v[102:103], v[10:13], off offset:1024 nt
	global_store_dwordx4 v[102:103], v[6:9], off offset:2048 nt
	global_store_dwordx4 v[102:103], v[2:5], off offset:3072 nt
	v_pk_fma_f32 v[14:15], v[14:15], v[78:79], v[46:47]
	v_pk_fma_f32 v[16:17], v[16:17], v[80:81], v[48:49]
	v_cvt_pk_bf16_f32 v14, v14, v15
	v_cvt_pk_bf16_f32 v15, v16, v17
	global_store_dwordx2 v[98:99], v[14:15], off offset:-2048 nt
	v_pk_add_f32 v[14:15], v[58:59], 1.0 op_sel_hi:[1,0]
	v_pk_add_f32 v[16:17], v[60:61], 1.0 op_sel_hi:[1,0]
	v_pk_fma_f32 v[10:11], v[10:11], v[14:15], v[42:43]
	v_pk_fma_f32 v[12:13], v[12:13], v[16:17], v[44:45]
	v_cvt_pk_bf16_f32 v10, v10, v11
	v_cvt_pk_bf16_f32 v11, v12, v13
	global_store_dwordx2 v[98:99], v[10:11], off offset:-1536 nt
	v_pk_add_f32 v[10:11], v[54:55], 1.0 op_sel_hi:[1,0]
	v_pk_add_f32 v[12:13], v[56:57], 1.0 op_sel_hi:[1,0]
	v_pk_fma_f32 v[6:7], v[6:7], v[10:11], v[38:39]
	v_pk_fma_f32 v[8:9], v[8:9], v[12:13], v[40:41]
	v_cvt_pk_bf16_f32 v6, v6, v7
	v_cvt_pk_bf16_f32 v7, v8, v9
	global_store_dwordx2 v[98:99], v[6:7], off offset:-1024 nt
	v_pk_add_f32 v[6:7], v[50:51], 1.0 op_sel_hi:[1,0]
	v_pk_add_f32 v[8:9], v[52:53], 1.0 op_sel_hi:[1,0]
	v_lshlrev_b64 v[106:107], 12, v[106:107]
	v_pk_fma_f32 v[2:3], v[2:3], v[6:7], v[34:35]
	v_pk_fma_f32 v[4:5], v[4:5], v[8:9], v[36:37]
	v_lshl_add_u64 v[106:107], v[108:109], 0, v[106:107]
	v_cvt_pk_bf16_f32 v2, v2, v3
	v_cvt_pk_bf16_f32 v3, v4, v5
	global_store_dwordx2 v[98:99], v[2:3], off offset:-512 nt
	v_lshl_add_u64 v[2:3], v[106:107], 0, v[0:1]
	global_store_dwordx4 v[2:3], v[30:33], off nt
	global_store_dwordx4 v[2:3], v[26:29], off offset:1024 nt
	global_store_dwordx4 v[2:3], v[22:25], off offset:2048 nt
	global_store_dwordx4 v[2:3], v[18:21], off offset:3072 nt
	v_pk_fma_f32 v[2:3], v[30:31], v[78:79], v[46:47]
	v_pk_fma_f32 v[4:5], v[32:33], v[80:81], v[48:49]
	v_cvt_pk_bf16_f32 v2, v2, v3
	v_cvt_pk_bf16_f32 v3, v4, v5
	global_store_dwordx2 v[98:99], v[2:3], off nt
	v_pk_fma_f32 v[2:3], v[26:27], v[14:15], v[42:43]
	v_pk_fma_f32 v[4:5], v[28:29], v[16:17], v[44:45]
	v_cvt_pk_bf16_f32 v2, v2, v3
	v_cvt_pk_bf16_f32 v3, v4, v5
	global_store_dwordx2 v[98:99], v[2:3], off offset:512 nt
	v_pk_fma_f32 v[2:3], v[22:23], v[10:11], v[38:39]
	v_pk_fma_f32 v[4:5], v[24:25], v[12:13], v[40:41]
	s_and_b64 s[0:1], exec, vcc
	v_cvt_pk_bf16_f32 v2, v2, v3
	v_cvt_pk_bf16_f32 v3, v4, v5
	s_or_b64 s[6:7], s[0:1], s[6:7]
	global_store_dwordx2 v[98:99], v[2:3], off offset:1024 nt
	v_pk_fma_f32 v[2:3], v[18:19], v[6:7], v[34:35]
	v_pk_fma_f32 v[4:5], v[20:21], v[8:9], v[36:37]
	v_readlane_b32 s0, v244, 31
	v_cvt_pk_bf16_f32 v2, v2, v3
	v_cvt_pk_bf16_f32 v3, v4, v5
	v_readlane_b32 s1, v244, 32
	global_store_dwordx2 v[98:99], v[2:3], off offset:1536 nt
	v_mov_b32_e32 v100, v101
	v_lshl_add_u64 v[98:99], v[98:99], 0, s[0:1]
	s_waitcnt vmcnt(0)
	v_mov_b64_e32 v[14:15], v[74:75]
	v_mov_b64_e32 v[16:17], v[76:77]
	v_mov_b64_e32 v[10:11], v[70:71]
	v_mov_b64_e32 v[12:13], v[72:73]
	v_mov_b64_e32 v[6:7], v[66:67]
	v_mov_b64_e32 v[8:9], v[68:69]
	v_mov_b64_e32 v[2:3], v[62:63]
	v_mov_b64_e32 v[4:5], v[64:65]
	v_mov_b64_e32 v[30:31], v[82:83]
	v_mov_b64_e32 v[32:33], v[84:85]
	v_mov_b64_e32 v[26:27], v[86:87]
	v_mov_b64_e32 v[28:29], v[88:89]
	v_mov_b64_e32 v[22:23], v[90:91]
	v_mov_b64_e32 v[24:25], v[92:93]
	v_mov_b64_e32 v[18:19], v[94:95]
	v_mov_b64_e32 v[20:21], v[96:97]
	s_andn2_b64 exec, exec, s[6:7]
	s_cbranch_execz .LBB0_785
